# SSM weight staging (global->LDS) unrolled: 12 loads in flight instead of 12 dependent round trips
# speedup vs baseline: 1.0046x; 1.0046x over previous
; #define LAS __attribute__((address_space(3)))
; template <bool PASS2>
; __device__ __forceinline__ void ssm_phase(const Params& p, const Frame& F0) {
;     ...
;         { const u32x4* src = (const u32x4*)((const bf16_t*)(p.ws + WS_SSMW) + (size_t)g * SSM_FRAG_ELEMS);
;           for (int e = F.tid; e < SSM_FRAG_ELEMS / 8; e += 512) ((LAS u32x4*)F.lds)[e] = src[e];
;           if (F.tid < 64) ((LAS f32x2*)(F.lds + SSM_M1_OFF))[F.tid] = ((const f32x2*)(p.ws + WS_M1))[g * 64 + F.tid]; }
;         __syncthreads();
.LBB0_523:
	global_load_dwordx4 v[4:7], v[0:1], off
	v_lshl_add_u64 v[0:1], v[0:1], 0, s[14:15]
	global_load_dwordx4 v[8:11], v[0:1], off
	v_lshl_add_u64 v[0:1], v[0:1], 0, s[14:15]
	global_load_dwordx4 v[12:15], v[0:1], off
	v_lshl_add_u64 v[0:1], v[0:1], 0, s[14:15]
	global_load_dwordx4 v[16:19], v[0:1], off
	v_lshl_add_u64 v[0:1], v[0:1], 0, s[14:15]
	global_load_dwordx4 v[20:23], v[0:1], off
	v_lshl_add_u64 v[0:1], v[0:1], 0, s[14:15]
	global_load_dwordx4 v[24:27], v[0:1], off
	v_lshl_add_u64 v[0:1], v[0:1], 0, s[14:15]
	global_load_dwordx4 v[28:31], v[0:1], off
	v_lshl_add_u64 v[0:1], v[0:1], 0, s[14:15]
	global_load_dwordx4 v[32:35], v[0:1], off
	v_lshl_add_u64 v[0:1], v[0:1], 0, s[14:15]
	global_load_dwordx4 v[44:47], v[0:1], off
	v_lshl_add_u64 v[0:1], v[0:1], 0, s[14:15]
	global_load_dwordx4 v[48:51], v[0:1], off
	v_lshl_add_u64 v[0:1], v[0:1], 0, s[14:15]
	global_load_dwordx4 v[52:55], v[0:1], off
	v_lshl_add_u64 v[0:1], v[0:1], 0, s[14:15]
	global_load_dwordx4 v[56:59], v[0:1], off
	v_add_u32_e32 v3, 0x10000, v2
	s_waitcnt vmcnt(11)
	ds_write_b128 v2, v[4:7]
	s_waitcnt vmcnt(10)
	ds_write_b128 v2, v[8:11] offset:8192
	s_waitcnt vmcnt(9)
	ds_write_b128 v2, v[12:15] offset:16384
	s_waitcnt vmcnt(8)
	ds_write_b128 v2, v[16:19] offset:24576
	s_waitcnt vmcnt(7)
	ds_write_b128 v2, v[20:23] offset:32768
	s_waitcnt vmcnt(6)
	ds_write_b128 v2, v[24:27] offset:40960
	s_waitcnt vmcnt(5)
	ds_write_b128 v2, v[28:31] offset:49152
	s_waitcnt vmcnt(4)
	ds_write_b128 v2, v[32:35] offset:57344
	s_waitcnt vmcnt(3)
	ds_write_b128 v3, v[44:47]
	s_waitcnt vmcnt(2)
	ds_write_b128 v3, v[48:51] offset:8192
	s_waitcnt vmcnt(1)
	ds_write_b128 v3, v[52:55] offset:16384
	s_waitcnt vmcnt(0)
	ds_write_b128 v3, v[56:59] offset:24576

; #define LAS __attribute__((address_space(3)))
; template <bool PASS2>
; __device__ __forceinline__ void ssm_phase(const Params& p, const Frame& F0) {
;     ...
;         { const u32x4* src = (const u32x4*)((const bf16_t*)(p.ws + WS_SSMW) + (size_t)g * SSM_FRAG_ELEMS);
;           for (int e = F.tid; e < SSM_FRAG_ELEMS / 8; e += 512) ((LAS u32x4*)F.lds)[e] = src[e];
;           if (F.tid < 64) ((LAS f32x2*)(F.lds + SSM_M1_OFF))[F.tid] = ((const f32x2*)(p.ws + WS_M1))[g * 64 + F.tid]; }
;         __syncthreads();
.LBB0_609:
	s_mov_b64 s[20:21], 0x2000
	global_load_dwordx4 v[26:29], v[2:3], off
	v_lshl_add_u64 v[2:3], v[2:3], 0, s[20:21]
	global_load_dwordx4 v[30:33], v[2:3], off
	v_lshl_add_u64 v[2:3], v[2:3], 0, s[20:21]
	global_load_dwordx4 v[34:37], v[2:3], off
	v_lshl_add_u64 v[2:3], v[2:3], 0, s[20:21]
	global_load_dwordx4 v[38:41], v[2:3], off
	v_lshl_add_u64 v[2:3], v[2:3], 0, s[20:21]
	global_load_dwordx4 v[42:45], v[2:3], off
	v_lshl_add_u64 v[2:3], v[2:3], 0, s[20:21]
	global_load_dwordx4 v[46:49], v[2:3], off
	v_lshl_add_u64 v[2:3], v[2:3], 0, s[20:21]
	global_load_dwordx4 v[50:53], v[2:3], off
	v_lshl_add_u64 v[2:3], v[2:3], 0, s[20:21]
	global_load_dwordx4 v[54:57], v[2:3], off
	v_lshl_add_u64 v[2:3], v[2:3], 0, s[20:21]
	global_load_dwordx4 v[58:61], v[2:3], off
	v_lshl_add_u64 v[2:3], v[2:3], 0, s[20:21]
	global_load_dwordx4 v[62:65], v[2:3], off
	v_lshl_add_u64 v[2:3], v[2:3], 0, s[20:21]
	global_load_dwordx4 v[66:69], v[2:3], off
	v_lshl_add_u64 v[2:3], v[2:3], 0, s[20:21]
	global_load_dwordx4 v[70:73], v[2:3], off
	v_add_u32_e32 v21, 0x10000, v1
	s_waitcnt vmcnt(11)
	ds_write_b128 v1, v[26:29]
	s_waitcnt vmcnt(10)
	ds_write_b128 v1, v[30:33] offset:8192
	s_waitcnt vmcnt(9)
	ds_write_b128 v1, v[34:37] offset:16384
	s_waitcnt vmcnt(8)
	ds_write_b128 v1, v[38:41] offset:24576
	s_waitcnt vmcnt(7)
	ds_write_b128 v1, v[42:45] offset:32768
	s_waitcnt vmcnt(6)
	ds_write_b128 v1, v[46:49] offset:40960
	s_waitcnt vmcnt(5)
	ds_write_b128 v1, v[50:53] offset:49152
	s_waitcnt vmcnt(4)
	ds_write_b128 v1, v[54:57] offset:57344
	s_waitcnt vmcnt(3)
	ds_write_b128 v21, v[58:61]
	s_waitcnt vmcnt(2)
	ds_write_b128 v21, v[62:65] offset:8192
	s_waitcnt vmcnt(1)
	ds_write_b128 v21, v[66:69] offset:16384
	s_waitcnt vmcnt(0)
	ds_write_b128 v21, v[70:73] offset:24576
